# attention loop unrolled by two on the n1 score register set: QK chain writes the set the exps are not reading, all score copies removed; V fragments in the freed K-fragment slots
# speedup vs baseline: 1.0299x; 1.0075x over previous
; __device__ __forceinline__ void attn_unit(const Params& P, unsigned char* lds, int h, int qb) {
;     ...
;         } else if (act) {
;             ATT_GAP(0, 32);
;         }
;         if (act) {
;             lsum += ps0 + ps1;
.LBB0_879:
	s_mov_b64 s[10:11], 0
	s_and_b64 vcc, exec, s[8:9]
	s_mov_b64 s[12:13], 0
	s_cbranch_vccz .LBB0_881
	v_mov_b64_e32 v[128:129], v[16:17]
	v_mov_b64_e32 v[130:131], v[18:19]
	v_mov_b64_e32 v[132:133], v[20:21]
	v_mov_b64_e32 v[134:135], v[22:23]
	v_mov_b64_e32 v[136:137], v[24:25]
	v_mov_b64_e32 v[138:139], v[26:27]
	v_mov_b64_e32 v[140:141], v[28:29]
	v_mov_b64_e32 v[142:143], v[30:31]
	s_bitcmp1_b32 s21, 0
	s_cbranch_scc1 .Lattn_l879
	v_mov_b64_e32 v[112:113], v[80:81]
	v_mov_b64_e32 v[114:115], v[82:83]
	v_mov_b64_e32 v[116:117], v[84:85]
	v_mov_b64_e32 v[118:119], v[86:87]
	v_mov_b64_e32 v[120:121], v[88:89]
	v_mov_b64_e32 v[122:123], v[90:91]
	v_mov_b64_e32 v[124:125], v[92:93]
	v_mov_b64_e32 v[126:127], v[94:95]
.Lattn_l879:
	v_mov_b32_e32 v2, v128
	v_mov_b32_e32 v4, v117
	v_exp_f32_e32 v11, v2
	v_mov_b32_e32 v2, v129
	s_mov_b64 s[12:13], -1
	v_exp_f32_e32 v223, v2
	v_mov_b32_e32 v2, v130
	v_exp_f32_e32 v219, v2
	v_mov_b32_e32 v2, v131
	v_exp_f32_e32 v225, v2
	v_mov_b32_e32 v2, v132
	v_exp_f32_e32 v13, v2
	v_mov_b32_e32 v2, v133
	v_exp_f32_e32 v15, v2
	v_mov_b32_e32 v2, v134
	v_exp_f32_e32 v181, v2
	v_mov_b32_e32 v2, v135
	v_exp_f32_e32 v183, v2
	v_mov_b32_e32 v2, v136
	v_exp_f32_e32 v209, v2
	v_mov_b32_e32 v2, v137
	v_cvt_pk_bf16_f32 v5, v181, v183
	v_exp_f32_e32 v211, v2
	v_mov_b32_e32 v2, v138
	v_exp_f32_e32 v213, v2
	v_mov_b32_e32 v2, v139
	v_cvt_pk_bf16_f32 v6, v209, v211
	v_exp_f32_e32 v215, v2
	v_mov_b32_e32 v2, v140
	v_exp_f32_e32 v217, v2
	v_mov_b32_e32 v2, v141
	v_cvt_pk_bf16_f32 v7, v213, v215
	v_exp_f32_e32 v221, v2
	v_mov_b32_e32 v2, v142
	v_exp_f32_e32 v227, v2
	v_mov_b32_e32 v2, v143
	v_cvt_pk_bf16_f32 v8, v217, v221
	v_exp_f32_e32 v229, v2
	v_mov_b32_e32 v2, v112
	v_exp_f32_e32 v10, v2
	v_mov_b32_e32 v2, v113
	v_cvt_pk_bf16_f32 v9, v227, v229
	v_exp_f32_e32 v222, v2
	v_mov_b32_e32 v2, v114
	v_exp_f32_e32 v218, v2
	v_mov_b32_e32 v2, v115
	v_exp_f32_e32 v224, v2
	v_mov_b32_e32 v2, v116
	v_exp_f32_e32 v12, v2
	v_pk_add_f32 v[2:3], v[10:11], 0 op_sel_hi:[1,0]
	v_exp_f32_e32 v14, v4
	v_mov_b32_e32 v4, v118
	v_pk_add_f32 v[2:3], v[2:3], v[222:223]
	v_exp_f32_e32 v180, v4
	v_mov_b32_e32 v4, v119
	v_pk_add_f32 v[2:3], v[2:3], v[218:219]
	v_exp_f32_e32 v182, v4
	v_mov_b32_e32 v4, v120
	v_pk_add_f32 v[2:3], v[2:3], v[224:225]
	v_exp_f32_e32 v208, v4
	v_mov_b32_e32 v4, v121
	v_pk_add_f32 v[2:3], v[2:3], v[12:13]
	v_exp_f32_e32 v210, v4
	v_mov_b32_e32 v4, v122
	v_pk_add_f32 v[2:3], v[2:3], v[14:15]
	v_exp_f32_e32 v212, v4
	v_mov_b32_e32 v4, v123
	v_pk_add_f32 v[2:3], v[2:3], v[180:181]
	v_exp_f32_e32 v214, v4
	v_mov_b32_e32 v4, v124
	v_pk_add_f32 v[2:3], v[2:3], v[182:183]
	v_cvt_pk_bf16_f32 v10, v10, v222
	v_pk_add_f32 v[2:3], v[2:3], v[208:209]
	v_exp_f32_e32 v216, v4
	v_mov_b32_e32 v4, v125
	v_pk_add_f32 v[2:3], v[2:3], v[210:211]
	v_cvt_pk_bf16_f32 v12, v12, v14
	v_pk_add_f32 v[2:3], v[2:3], v[212:213]
	v_exp_f32_e32 v220, v4
	v_mov_b32_e32 v4, v126
	v_pk_add_f32 v[2:3], v[2:3], v[214:215]
	v_cvt_pk_bf16_f32 v181, v212, v214
	v_pk_add_f32 v[2:3], v[2:3], v[216:217]
	v_exp_f32_e32 v226, v4
	v_pk_add_f32 v[2:3], v[2:3], v[220:221]
	v_mov_b32_e32 v4, v127
	v_pk_add_f32 v[2:3], v[2:3], v[226:227]
	v_exp_f32_e32 v228, v4
	v_cvt_pk_bf16_f32 v4, v13, v15
	v_pk_add_f32 v[230:231], v[2:3], v[228:229]
	v_cvt_pk_bf16_f32 v2, v11, v223
	v_cvt_pk_bf16_f32 v3, v219, v225
	v_cvt_pk_bf16_f32 v11, v218, v224
	v_cvt_pk_bf16_f32 v13, v180, v182
	v_cvt_pk_bf16_f32 v180, v208, v210
	v_cvt_pk_bf16_f32 v182, v216, v220
	v_cvt_pk_bf16_f32 v183, v226, v228
	s_add_i32 s25, s21, 1
	s_and_b64 vcc, exec, s[10:11]
	s_cbranch_vccz .LBB0_893
	s_branch .LBB0_882

; #define SBAR() __builtin_amdgcn_sched_barrier(0)
; __device__ __forceinline__ void attn_unit(const Params& P, unsigned char* lds, int h, int qb) {
;     ...
;         if (act && actn) {
;             const unsigned char* Kn = lds + ((t + 1) & 1) * KBUF + r32 * KROW + hi * 16;
;             SBAR();
; #pragma unroll
;             for (int g = 0; g < 6; ++g) {
;                 const bf16x8 ka = *(const bf16x8*)(Kn + g * 32), kb = *(const bf16x8*)(Kn + 32 * KROW + g * 32);
;                 n0 = __builtin_amdgcn_mfma_f32_32x32x16_bf16(ka, qr[g], g == 0 ? negm : n0, 0, 0, 0);
;                 SBAR();
;                 ATT_GAP((32 * (2 * g)) / 12, (32 * (2 * g + 1)) / 12);
;                 SBAR();
;                 n1 = __builtin_amdgcn_mfma_f32_32x32x16_bf16(kb, qr[g], g == 0 ? negm : n1, 0, 0, 0);
;                 SBAR();
;                 ATT_GAP((32 * (2 * g + 1)) / 12, (32 * (2 * g + 2)) / 12);
;                 SBAR();
;             }
;             if ((t + 1) * 64 + 63 > qw0) attn_mask(n0, n1, (t + 1) * 64, qg, hi);
;         } else if (act) {
;             ATT_GAP(0, 32);
;         }
;         if (act) {
;             lsum += ps0 + ps1;
;             const unsigned char* Vb = lds + 2 * KBUF + (t & 1) * VBUF;
; #pragma unroll
;             for (int ks = 0; ks < 4; ++ks) {
;                 const bf16x8 pa = __builtin_bit_cast(bf16x8, pw[ks]);
;                 const unsigned char* va = Vb + r32 * VROW + (16 * ks + 4 * hi) * 2;
;                 const v2u l0 = *(const v2u*)va, h0 = *(const v2u*)(va + 16);
;                 const v2u l1 = *(const v2u*)(va + 32 * VROW), h1 = *(const v2u*)(va + 32 * VROW + 16);
;                 const bf16x8 vf0 = __builtin_bit_cast(bf16x8, ((v4u){l0.x, l0.y, h0.x, h0.y}));
;                 const bf16x8 vf1 = __builtin_bit_cast(bf16x8, ((v4u){l1.x, l1.y, h1.x, h1.y}));
;                 o0 = __builtin_amdgcn_mfma_f32_32x32x16_bf16(vf0, pa, o0, 0, 0, 0);
;                 o1 = __builtin_amdgcn_mfma_f32_32x32x16_bf16(vf1, pa, o1, 0, 0, 0);
;             }
;         }
.LBB0_884:
	s_bitcmp1_b32 s21, 0
	s_cselect_b32 s8, 0x2200, 0
	v_add_u32_e32 v142, s8, v250
	v_add_u32_e32 v143, 0x7800, v142
	v_add_u32_e32 v142, 0x6800, v142
	ds_read2_b64 v[210:213], v142 offset1:2
	ds_read2_b64 v[214:217], v143 offset0:32 offset1:34
	ds_read2_b64 v[218:221], v142 offset0:4 offset1:6
	ds_read2_b64 v[222:225], v143 offset0:36 offset1:38
	v_add_f32_e32 v14, v14, v128
	v_add_f32_e32 v15, v15, v129
	v_add_f32_e32 v14, v14, v130
	v_add_f32_e32 v15, v15, v131
	v_add_f32_e32 v14, v14, v132
	v_add_f32_e32 v15, v15, v133
	v_add_f32_e32 v14, v14, v134
	v_add_f32_e32 v15, v15, v135
	v_add_f32_e32 v14, v14, v136
	v_add_f32_e32 v15, v15, v137
	v_add_f32_e32 v14, v14, v138
	v_add_f32_e32 v15, v15, v139
	v_add_f32_e32 v14, v14, v140
	v_add_f32_e32 v15, v15, v141
	ds_read2_b64 v[128:131], v142 offset0:8 offset1:10
	ds_read2_b64 v[132:135], v143 offset0:40 offset1:42
	ds_read2_b64 v[136:139], v142 offset0:12 offset1:14
	s_waitcnt lgkmcnt(6)
	v_mfma_f32_32x32x16_bf16 v[48:63], v[210:213], v[2:5], v[48:63]
	v_max3_f32 v140, v16, v17, v80
	v_max3_f32 v141, v81, v18, v19
	v_add_f32_e32 v14, v14, v96
	v_add_f32_e32 v15, v15, v97
	s_waitcnt lgkmcnt(5)
	v_mfma_f32_32x32x16_bf16 v[32:47], v[214:217], v[2:5], v[32:47]
	ds_read2_b64 v[210:213], v143 offset0:44 offset1:46
	v_max3_f32 v140, v140, v82, v83
	v_add_f32_e32 v14, v14, v98
	v_add_f32_e32 v15, v15, v99
	v_max3_f32 v141, v141, v20, v21
	s_waitcnt lgkmcnt(5)
	v_mfma_f32_32x32x16_bf16 v[48:63], v[218:221], v[6:9], v[48:63]
	v_add_f32_e32 v14, v14, v100
	v_add_f32_e32 v15, v15, v101
	v_max3_f32 v140, v140, v84, v85
	v_add_f32_e32 v14, v14, v102
	v_add_f32_e32 v15, v15, v103
	s_waitcnt lgkmcnt(4)
	v_mfma_f32_32x32x16_bf16 v[32:47], v[222:225], v[6:9], v[32:47]
	v_max3_f32 v141, v141, v22, v23
	v_add_f32_e32 v14, v14, v104
	v_add_f32_e32 v15, v15, v105
	v_max3_f32 v140, v140, v86, v87
	s_waitcnt lgkmcnt(3)
	v_mfma_f32_32x32x16_bf16 v[48:63], v[128:131], v[10:13], v[48:63]
	v_add_f32_e32 v14, v14, v106
	v_add_f32_e32 v15, v15, v107
	v_max3_f32 v141, v141, v24, v25
	v_add_f32_e32 v14, v14, v108
	v_add_f32_e32 v15, v15, v109
	s_waitcnt lgkmcnt(2)
	v_mfma_f32_32x32x16_bf16 v[32:47], v[132:135], v[10:13], v[32:47]
	v_max3_f32 v140, v140, v88, v89
	v_add_f32_e32 v14, v14, v110
	v_add_f32_e32 v15, v15, v111
	v_max3_f32 v141, v141, v26, v27
	s_waitcnt lgkmcnt(1)
	v_mfma_f32_32x32x16_bf16 v[48:63], v[136:139], v[180:183], v[48:63]
	v_max3_f32 v140, v140, v90, v91
	v_max3_f32 v141, v141, v28, v29
	v_max3_f32 v140, v140, v92, v93
	s_waitcnt lgkmcnt(0)
	v_mfma_f32_32x32x16_bf16 v[32:47], v[210:213], v[180:183], v[32:47]
	v_max3_f32 v141, v141, v30, v31
	v_max3_f32 v140, v140, v94, v95
	v_max_f32_e32 v98, v140, v141
	v_add_f32_e32 v96, v14, v15
	v_add_f32_e32 v236, v236, v96
	s_branch .LBB0_896
.Lattn_e882:
	s_waitcnt lgkmcnt(3)
	v_mfma_f32_32x32x16_bf16 v[112:127], v[210:213], v[160:163], v[64:79]
	v_exp_f32_e32 v15, v16
	v_exp_f32_e32 v97, v17
	v_exp_f32_e32 v99, v18
	v_cvt_pk_bf16_f32 v2, v15, v97
	ds_read_b128 v[210:213], v208 offset:6784
	s_waitcnt lgkmcnt(3)
	v_mfma_f32_32x32x16_bf16 v[112:127], v[214:217], v[144:147], v[112:127]
	v_exp_f32_e32 v101, v19
	v_exp_f32_e32 v103, v20
	v_cvt_pk_bf16_f32 v3, v99, v101
	v_exp_f32_e32 v105, v21
	ds_read_b128 v[214:217], v208 offset:6816
	s_waitcnt lgkmcnt(3)
	v_mfma_f32_32x32x16_bf16 v[112:127], v[218:221], v[148:151], v[112:127]
	v_exp_f32_e32 v107, v22
	v_cvt_pk_bf16_f32 v4, v103, v105
	v_exp_f32_e32 v109, v23
	v_exp_f32_e32 v111, v24
	ds_read_b128 v[218:221], v208
	s_waitcnt lgkmcnt(3)
	v_mfma_f32_32x32x16_bf16 v[112:127], v[222:225], v[152:155], v[112:127]
	v_cvt_pk_bf16_f32 v5, v107, v109
	v_exp_f32_e32 v129, v25
	v_exp_f32_e32 v131, v26
	v_cvt_pk_bf16_f32 v6, v111, v129
	ds_read_b128 v[222:225], v208 offset:32
	s_waitcnt lgkmcnt(3)
	v_mfma_f32_32x32x16_bf16 v[112:127], v[210:213], v[156:159], v[112:127]
	v_exp_f32_e32 v133, v27
	v_exp_f32_e32 v135, v28
	v_cvt_pk_bf16_f32 v7, v131, v133
	v_exp_f32_e32 v137, v29
	ds_read_b128 v[210:213], v208 offset:64
	s_waitcnt lgkmcnt(3)
	v_mfma_f32_32x32x16_bf16 v[112:127], v[214:217], v[164:167], v[112:127]
	v_exp_f32_e32 v139, v30
	v_cvt_pk_bf16_f32 v8, v135, v137
	v_exp_f32_e32 v141, v31
	v_exp_f32_e32 v14, v80
	ds_read_b128 v[214:217], v208 offset:96
	s_waitcnt lgkmcnt(3)
	v_mfma_f32_32x32x16_bf16 v[16:31], v[218:221], v[160:163], v[64:79]
	v_cvt_pk_bf16_f32 v9, v139, v141
	v_exp_f32_e32 v96, v81
	v_exp_f32_e32 v98, v82
	v_cvt_pk_bf16_f32 v10, v14, v96
	ds_read_b128 v[218:221], v208 offset:128
	s_waitcnt lgkmcnt(3)
	v_mfma_f32_32x32x16_bf16 v[16:31], v[222:225], v[144:147], v[16:31]
	v_exp_f32_e32 v100, v83
	v_exp_f32_e32 v102, v84
	v_cvt_pk_bf16_f32 v11, v98, v100
	v_exp_f32_e32 v104, v85
	ds_read_b128 v[222:225], v208 offset:160
	s_waitcnt lgkmcnt(3)
	v_mfma_f32_32x32x16_bf16 v[16:31], v[210:213], v[148:151], v[16:31]
	v_exp_f32_e32 v106, v86
	v_cvt_pk_bf16_f32 v12, v102, v104
	v_exp_f32_e32 v108, v87
	v_exp_f32_e32 v110, v88
	s_waitcnt lgkmcnt(2)
	v_mfma_f32_32x32x16_bf16 v[16:31], v[214:217], v[152:155], v[16:31]
	v_cvt_pk_bf16_f32 v13, v106, v108
	v_exp_f32_e32 v128, v89
	v_exp_f32_e32 v130, v90
	v_cvt_pk_bf16_f32 v180, v110, v128
	s_waitcnt lgkmcnt(1)
	v_mfma_f32_32x32x16_bf16 v[16:31], v[218:221], v[156:159], v[16:31]
	v_exp_f32_e32 v132, v91
	v_exp_f32_e32 v134, v92
	v_cvt_pk_bf16_f32 v181, v130, v132
	v_exp_f32_e32 v136, v93
	s_waitcnt lgkmcnt(0)
	v_mfma_f32_32x32x16_bf16 v[16:31], v[222:225], v[164:167], v[16:31]
	v_exp_f32_e32 v138, v94
	v_cvt_pk_bf16_f32 v182, v134, v136
	v_exp_f32_e32 v140, v95
	s_cmp_le_i32 s20, s15
	v_cvt_pk_bf16_f32 v183, v138, v140
	s_cbranch_scc1 .Lattn_e884
; __device__ __forceinline__ int crow(int r, int hi) { return (r & 3) + 8 * (r >> 2) + 4 * hi; }
; __device__ __forceinline__ void attn_mask(f32x16& s0, f32x16& s1, int k0, int qg, int hi) {
; #pragma unroll
;     for (int r = 0; r < 16; ++r) { const int key = k0 + crow(r, hi); if (key > qg) s0[r] = -1e30f; if (key + 32 > qg) s1[r] = -1e30f; }
; }
; __device__ __forceinline__ void attn_unit(const Params& P, unsigned char* lds, int h, int qb) {
;     ...
;             if ((t + 1) * 64 + 63 > qw0) attn_mask(n0, n1, (t + 1) * 64, qg, hi);
;         } else if (act) {
;             ATT_GAP(0, 32);
;         }
;         if (act) {
;             lsum += ps0 + ps1;
;             const unsigned char* Vb = lds + 2 * KBUF + (t & 1) * VBUF;
; #pragma unroll
;             for (int ks = 0; ks < 4; ++ks) {
;                 const bf16x8 pa = __builtin_bit_cast(bf16x8, pw[ks]);
;                 const unsigned char* va = Vb + r32 * VROW + (16 * ks + 4 * hi) * 2;
;                 const v2u l0 = *(const v2u*)va, h0 = *(const v2u*)(va + 16);
;                 const v2u l1 = *(const v2u*)(va + 32 * VROW), h1 = *(const v2u*)(va + 32 * VROW + 16);
;                 const bf16x8 vf0 = __builtin_bit_cast(bf16x8, ((v4u){l0.x, l0.y, h0.x, h0.y}));
;                 const bf16x8 vf1 = __builtin_bit_cast(bf16x8, ((v4u){l1.x, l1.y, h1.x, h1.y}));
;                 o0 = __builtin_amdgcn_mfma_f32_32x32x16_bf16(vf0, pa, o0, 0, 0, 0);
;                 o1 = __builtin_amdgcn_mfma_f32_32x32x16_bf16(vf1, pa, o1, 0, 0, 0);
;             }
;         }
	s_nop 3
	v_add_u32_e32 v226, s20, v249
	v_subrev_u32_e32 v228, 31, v226
	v_subrev_u32_e32 v227, 63, v226
	v_cmp_le_i32_e32 vcc, v228, v198
	s_nop 1
	v_cndmask_b32_e32 v112, v244, v112, vcc
	v_cmp_lt_i32_e32 vcc, v227, v198
	s_nop 1
	v_cndmask_b32_e32 v17, v244, v17, vcc
	v_cmp_le_i32_e32 vcc, v227, v198
	v_subrev_u32_e32 v227, 30, v226
	s_nop 0
	v_cndmask_b32_e32 v16, v244, v16, vcc
	v_cmp_le_i32_e32 vcc, v227, v198
	v_subrev_u32_e32 v227, 61, v226
	s_nop 0
	v_cndmask_b32_e32 v113, v244, v113, vcc
	v_cmp_le_i32_e32 vcc, v227, v198
	v_subrev_u32_e32 v227, 29, v226
	s_nop 0
	v_cndmask_b32_e32 v18, v244, v18, vcc
	v_cmp_le_i32_e32 vcc, v227, v198
	v_subrev_u32_e32 v227, 60, v226
	s_nop 0
	v_cndmask_b32_e32 v114, v244, v114, vcc
	v_cmp_le_i32_e32 vcc, v227, v198
	v_subrev_u32_e32 v227, 28, v226
	s_nop 0
	v_cndmask_b32_e32 v19, v244, v19, vcc
	v_cmp_le_i32_e32 vcc, v227, v198
	v_subrev_u32_e32 v227, 55, v226
	s_nop 0
	v_cndmask_b32_e32 v115, v244, v115, vcc
	v_cmp_le_i32_e32 vcc, v227, v198
	v_subrev_u32_e32 v227, 23, v226
	s_nop 0
	v_cndmask_b32_e32 v20, v244, v20, vcc
	v_cmp_le_i32_e32 vcc, v227, v198
	v_subrev_u32_e32 v227, 54, v226
	s_nop 0
	v_cndmask_b32_e32 v116, v244, v116, vcc
	v_cmp_le_i32_e32 vcc, v227, v198
	v_subrev_u32_e32 v227, 22, v226
	s_nop 0
	v_cndmask_b32_e32 v21, v244, v21, vcc
	v_cmp_le_i32_e32 vcc, v227, v198
	v_subrev_u32_e32 v227, 53, v226
	s_nop 0
	v_cndmask_b32_e32 v117, v244, v117, vcc
	v_cmp_le_i32_e32 vcc, v227, v198
	v_subrev_u32_e32 v227, 21, v226
	s_nop 0
	v_cndmask_b32_e32 v22, v244, v22, vcc
	v_cmp_le_i32_e32 vcc, v227, v198
	v_subrev_u32_e32 v227, 52, v226
	s_nop 0
	v_cndmask_b32_e32 v118, v244, v118, vcc
	v_cmp_le_i32_e32 vcc, v227, v198
	v_subrev_u32_e32 v227, 20, v226
	s_nop 0
	v_cndmask_b32_e32 v23, v244, v23, vcc
	v_cmp_le_i32_e32 vcc, v227, v198
	v_subrev_u32_e32 v227, 47, v226
	s_nop 0
	v_cndmask_b32_e32 v119, v244, v119, vcc
	v_cmp_le_i32_e32 vcc, v227, v198
	v_add_u32_e32 v227, -15, v226
	s_nop 0
	v_cndmask_b32_e32 v24, v244, v24, vcc
	v_cmp_le_i32_e32 vcc, v227, v198
	v_subrev_u32_e32 v227, 46, v226
	s_nop 0
	v_cndmask_b32_e32 v120, v244, v120, vcc
	v_cmp_le_i32_e32 vcc, v227, v198
	v_add_u32_e32 v227, -14, v226
	s_nop 0
	v_cndmask_b32_e32 v25, v244, v25, vcc
	v_cmp_le_i32_e32 vcc, v227, v198
	v_subrev_u32_e32 v227, 45, v226
	s_nop 0
	v_cndmask_b32_e32 v121, v244, v121, vcc
	v_cmp_le_i32_e32 vcc, v227, v198
	v_add_u32_e32 v227, -13, v226
	s_nop 0
	v_cndmask_b32_e32 v26, v244, v26, vcc
	v_cmp_le_i32_e32 vcc, v227, v198
	v_subrev_u32_e32 v227, 44, v226
	s_nop 0
	v_cndmask_b32_e32 v122, v244, v122, vcc
	v_cmp_le_i32_e32 vcc, v227, v198
	v_add_u32_e32 v227, -12, v226
	s_nop 0
	v_cndmask_b32_e32 v27, v244, v27, vcc
	v_cmp_le_i32_e32 vcc, v227, v198
	v_subrev_u32_e32 v227, 39, v226
	s_nop 0
	v_cndmask_b32_e32 v123, v244, v123, vcc
	v_cmp_le_i32_e32 vcc, v227, v198
	v_add_u32_e32 v227, -7, v226
	s_nop 0
	v_cndmask_b32_e32 v28, v244, v28, vcc
	v_cmp_le_i32_e32 vcc, v227, v198
	v_subrev_u32_e32 v227, 38, v226
	s_nop 0
	v_cndmask_b32_e32 v124, v244, v124, vcc
	v_cmp_le_i32_e32 vcc, v227, v198
	v_add_u32_e32 v227, -6, v226
	s_nop 0
	v_cndmask_b32_e32 v29, v244, v29, vcc
	v_cmp_le_i32_e32 vcc, v227, v198
	v_subrev_u32_e32 v227, 37, v226
	s_nop 0
	v_cndmask_b32_e32 v125, v244, v125, vcc
	v_cmp_le_i32_e32 vcc, v227, v198
	v_add_u32_e32 v227, -5, v226
	s_nop 0
	v_cndmask_b32_e32 v30, v244, v30, vcc
	v_cmp_le_i32_e32 vcc, v227, v198
	v_subrev_u32_e32 v227, 36, v226
	v_add_u32_e32 v226, -4, v226
	v_cndmask_b32_e32 v126, v244, v126, vcc
	v_cmp_le_i32_e32 vcc, v227, v198
	s_nop 1
	v_cndmask_b32_e32 v31, v244, v31, vcc
	v_cmp_le_i32_e32 vcc, v226, v198
	s_nop 1
	v_cndmask_b32_e32 v127, v244, v127, vcc
.Lattn_e884:
	s_bitcmp1_b32 s21, 0
	s_cselect_b32 s8, 0x2200, 0
	v_add_u32_e32 v142, s8, v250
	v_add_u32_e32 v143, 0x7800, v142
	v_add_u32_e32 v142, 0x6800, v142
	ds_read2_b64 v[210:213], v142 offset1:2
	ds_read2_b64 v[214:217], v143 offset0:32 offset1:34
	ds_read2_b64 v[218:221], v142 offset0:4 offset1:6
	ds_read2_b64 v[222:225], v143 offset0:36 offset1:38
	v_add_f32_e32 v14, v14, v128
	v_add_f32_e32 v15, v15, v129
	v_add_f32_e32 v14, v14, v130
	v_add_f32_e32 v15, v15, v131
	v_add_f32_e32 v14, v14, v132
	v_add_f32_e32 v15, v15, v133
	v_add_f32_e32 v14, v14, v134
	v_add_f32_e32 v15, v15, v135
	v_add_f32_e32 v14, v14, v136
	v_add_f32_e32 v15, v15, v137
	v_add_f32_e32 v14, v14, v138
	v_add_f32_e32 v15, v15, v139
	v_add_f32_e32 v14, v14, v140
	v_add_f32_e32 v15, v15, v141
	ds_read2_b64 v[128:131], v142 offset0:8 offset1:10
	ds_read2_b64 v[132:135], v143 offset0:40 offset1:42
	ds_read2_b64 v[136:139], v142 offset0:12 offset1:14
	s_waitcnt lgkmcnt(6)
	v_mfma_f32_32x32x16_bf16 v[48:63], v[210:213], v[2:5], v[48:63]
	v_max3_f32 v140, v16, v17, v112
	v_max3_f32 v141, v113, v18, v19
	v_add_f32_e32 v14, v14, v96
	v_add_f32_e32 v15, v15, v97
	s_waitcnt lgkmcnt(5)
	v_mfma_f32_32x32x16_bf16 v[32:47], v[214:217], v[2:5], v[32:47]
	ds_read2_b64 v[210:213], v143 offset0:44 offset1:46
	v_max3_f32 v140, v140, v114, v115
	v_add_f32_e32 v14, v14, v98
	v_add_f32_e32 v15, v15, v99
	v_max3_f32 v141, v141, v20, v21
	s_waitcnt lgkmcnt(5)
	v_mfma_f32_32x32x16_bf16 v[48:63], v[218:221], v[6:9], v[48:63]
	v_add_f32_e32 v14, v14, v100
	v_add_f32_e32 v15, v15, v101
	v_max3_f32 v140, v140, v116, v117
	v_add_f32_e32 v14, v14, v102
	v_add_f32_e32 v15, v15, v103
	s_waitcnt lgkmcnt(4)
	v_mfma_f32_32x32x16_bf16 v[32:47], v[222:225], v[6:9], v[32:47]
	v_max3_f32 v141, v141, v22, v23
	v_add_f32_e32 v14, v14, v104
	v_add_f32_e32 v15, v15, v105
	v_max3_f32 v140, v140, v118, v119
	s_waitcnt lgkmcnt(3)
	v_mfma_f32_32x32x16_bf16 v[48:63], v[128:131], v[10:13], v[48:63]
	v_add_f32_e32 v14, v14, v106
	v_add_f32_e32 v15, v15, v107
	v_max3_f32 v141, v141, v24, v25
	v_add_f32_e32 v14, v14, v108
	v_add_f32_e32 v15, v15, v109
	s_waitcnt lgkmcnt(2)
	v_mfma_f32_32x32x16_bf16 v[32:47], v[132:135], v[10:13], v[32:47]
	v_max3_f32 v140, v140, v120, v121
	v_add_f32_e32 v14, v14, v110
	v_add_f32_e32 v15, v15, v111
	v_max3_f32 v141, v141, v26, v27
	s_waitcnt lgkmcnt(1)
	v_mfma_f32_32x32x16_bf16 v[48:63], v[136:139], v[180:183], v[48:63]
	v_max3_f32 v140, v140, v122, v123
	v_max3_f32 v141, v141, v28, v29
	v_max3_f32 v140, v140, v124, v125
	s_waitcnt lgkmcnt(0)
	v_mfma_f32_32x32x16_bf16 v[32:47], v[210:213], v[180:183], v[32:47]
	v_max3_f32 v141, v141, v30, v31
	v_max3_f32 v140, v140, v126, v127
	v_max_f32_e32 v98, v140, v141
	v_add_f32_e32 v96, v14, v15
	v_add_f32_e32 v236, v236, v96
	s_branch .LBB0_896

; __device__ __forceinline__ void attn_unit(const Params& P, unsigned char* lds, int h, int qb) {
;     ...
;             if (t == 0 || __any(mx > THR)) {
;                 const float dl = (t == 0) ? mx : fmaxf(mx, 0.f), f = __builtin_amdgcn_exp2f(-dl);
;                 m += dl; lsum *= f;
; #pragma unroll
;                 for (int r = 0; r < 16; ++r) { c0[r] -= dl; c1[r] -= dl; o0[r] *= f; o1[r] *= f; negm[r] = -m; }
;             }
;         }
;     ...
;         c0 = n0; c1 = n1;
.LBB0_888:
	s_cbranch_execz .LBB0_891
	v_exp_f32_e64 v4, -v2
	v_add_f32_e32 v0, v0, v2
	v_xor_b32_e32 v96, 0x80000000, v0
	v_sub_f32_e32 v31, v31, v2
	v_sub_f32_e32 v30, v30, v2
	v_sub_f32_e32 v29, v29, v2
	v_sub_f32_e32 v28, v28, v2
	v_sub_f32_e32 v27, v27, v2
	v_sub_f32_e32 v26, v26, v2
	v_sub_f32_e32 v25, v25, v2
	v_sub_f32_e32 v24, v24, v2
	v_sub_f32_e32 v23, v23, v2
	v_sub_f32_e32 v22, v22, v2
	v_sub_f32_e32 v21, v21, v2
	v_sub_f32_e32 v20, v20, v2
	v_sub_f32_e32 v19, v19, v2
	v_sub_f32_e32 v18, v18, v2
	v_sub_f32_e32 v17, v17, v2
	v_sub_f32_e32 v16, v16, v2
	v_sub_f32_e32 v127, v127, v2
	v_sub_f32_e32 v126, v126, v2
	v_sub_f32_e32 v125, v125, v2
	v_sub_f32_e32 v124, v124, v2
	v_sub_f32_e32 v123, v123, v2
	v_sub_f32_e32 v122, v122, v2
	v_sub_f32_e32 v121, v121, v2
	v_sub_f32_e32 v120, v120, v2
	v_sub_f32_e32 v119, v119, v2
	v_sub_f32_e32 v118, v118, v2
	v_sub_f32_e32 v117, v117, v2
	v_sub_f32_e32 v116, v116, v2
	v_sub_f32_e32 v115, v115, v2
	v_sub_f32_e32 v114, v114, v2
	v_sub_f32_e32 v113, v113, v2
	v_sub_f32_e32 v112, v112, v2
	v_sub_f32_e32 v80, v80, v2
	v_sub_f32_e32 v81, v81, v2
	v_sub_f32_e32 v82, v82, v2
	v_sub_f32_e32 v83, v83, v2
	v_sub_f32_e32 v84, v84, v2
	v_sub_f32_e32 v85, v85, v2
	v_sub_f32_e32 v86, v86, v2
	v_sub_f32_e32 v87, v87, v2
	v_sub_f32_e32 v88, v88, v2
	v_sub_f32_e32 v89, v89, v2
	v_sub_f32_e32 v90, v90, v2
	v_sub_f32_e32 v91, v91, v2
	v_sub_f32_e32 v92, v92, v2
	v_sub_f32_e32 v93, v93, v2
	v_sub_f32_e32 v94, v94, v2
	v_sub_f32_e32 v95, v95, v2
	v_pk_mul_f32 v[62:63], v[62:63], v[4:5] op_sel_hi:[1,0]
	v_pk_mul_f32 v[60:61], v[60:61], v[4:5] op_sel_hi:[1,0]
	v_pk_mul_f32 v[58:59], v[58:59], v[4:5] op_sel_hi:[1,0]
	v_pk_mul_f32 v[56:57], v[56:57], v[4:5] op_sel_hi:[1,0]
	v_pk_mul_f32 v[54:55], v[54:55], v[4:5] op_sel_hi:[1,0]
	v_pk_mul_f32 v[52:53], v[52:53], v[4:5] op_sel_hi:[1,0]
	v_pk_mul_f32 v[50:51], v[50:51], v[4:5] op_sel_hi:[1,0]
	v_pk_mul_f32 v[48:49], v[48:49], v[4:5] op_sel_hi:[1,0]
	v_pk_mul_f32 v[46:47], v[46:47], v[4:5] op_sel_hi:[1,0]
	v_pk_mul_f32 v[44:45], v[44:45], v[4:5] op_sel_hi:[1,0]
	v_pk_mul_f32 v[42:43], v[42:43], v[4:5] op_sel_hi:[1,0]
	v_pk_mul_f32 v[40:41], v[40:41], v[4:5] op_sel_hi:[1,0]
	v_pk_mul_f32 v[38:39], v[38:39], v[4:5] op_sel_hi:[1,0]
	v_pk_mul_f32 v[36:37], v[36:37], v[4:5] op_sel_hi:[1,0]
	v_pk_mul_f32 v[34:35], v[34:35], v[4:5] op_sel_hi:[1,0]
	v_pk_mul_f32 v[32:33], v[32:33], v[4:5] op_sel_hi:[1,0]
	v_mul_f32_e32 v236, v236, v4
	v_mov_b32_e32 v97, v96
	v_mov_b32_e32 v98, v96
	v_mov_b32_e32 v99, v96
	v_mov_b32_e32 v100, v96
	v_mov_b32_e32 v101, v96
	v_mov_b32_e32 v102, v96
	v_mov_b32_e32 v103, v96
	v_mov_b32_e32 v104, v96
	v_mov_b32_e32 v105, v96
	v_mov_b32_e32 v106, v96
	v_mov_b32_e32 v107, v96
	v_mov_b32_e32 v108, v96
	v_mov_b32_e32 v109, v96
	v_mov_b32_e32 v110, v96
	v_mov_b32_e32 v111, v96
	v_mov_b32_e32 v79, v96
	v_mov_b32_e32 v78, v96
	v_mov_b32_e32 v77, v96
	v_mov_b32_e32 v76, v96
	v_mov_b32_e32 v75, v96
	v_mov_b32_e32 v74, v96
	v_mov_b32_e32 v73, v96
	v_mov_b32_e32 v72, v96
	v_mov_b32_e32 v71, v96
	v_mov_b32_e32 v70, v96
	v_mov_b32_e32 v69, v96
	v_mov_b32_e32 v68, v96
	v_mov_b32_e32 v67, v96
	v_mov_b32_e32 v66, v96
	v_mov_b32_e32 v65, v96
	v_mov_b32_e32 v64, v96
	s_cmp_ge_i32 s21, s18
	s_cbranch_scc1 .LBB0_879
	s_branch .LBB0_892
.LBB0_890:
.LBB0_891:
	s_cmp_ge_i32 s21, s18
	s_cbranch_scc1 .LBB0_879
.LBB0_892:
	s_mov_b64 s[12:13], 0
	s_add_i32 s25, s21, 1
	s_bitcmp1_b32 s21, 0
	s_cbranch_scc0 .Lattn_e882
	s_branch .LBB0_882
